# adds LDS-read hoisting (rescheduler) to the wkv T_II forward substitution block and the peeled last scan group
# speedup vs baseline: 1.1177x; 1.0021x over previous
.LBB0_812:
	s_or_saveexec_b64 s[0:1], s[80:81]
	v_lshlrev_b32_e32 v61, 1, v135
	s_xor_b64 exec, exec, s[0:1]
	s_cbranch_execz .LBB0_814
	v_lshl_add_u32 v40, v42, 1, 0
	v_mad_u32_u24 v51, v42, s96, v40
	v_add_u32_e32 v70, 0xfc00, v51
	ds_read2_b32 v[72:73], v70 offset0:36 offset1:72
	v_add_u32_e32 v71, 0x400, v70
	ds_read2_b32 v[76:77], v71 offset0:72 offset1:108
	v_add_u32_e32 v71, 0xf800, v51
	ds_read2_b64 v[80:83], v71 offset0:182 offset1:200
	ds_read_b96 v[84:86], v51 offset:65232
	ds_read_b96 v[88:90], v51 offset:65376
	ds_read_b128 v[92:95], v51 offset:65520
	ds_read_b128 v[96:99], v70 offset:1152
	v_cmp_eq_u32_e32 vcc, 0, v135
	ds_read_b128 v[100:103], v70 offset:1296
	v_cndmask_b32_e64 v41, 0, 1.0, vcc
	s_waitcnt lgkmcnt(7)
	v_lshlrev_b32_e32 v42, 16, v72
	ds_read_b128 v[104:107], v70 offset:1440
	v_cmp_eq_u32_e32 vcc, 1, v135
	v_lshlrev_b32_e32 v45, 16, v73
	s_waitcnt lgkmcnt(6)
	v_lshlrev_b32_e32 v46, 16, v80
	v_cndmask_b32_e64 v44, 0, 1.0, vcc
	v_cmp_eq_u32_e32 vcc, 2, v135
	v_fmac_f32_e32 v44, v41, v42
	s_nop 0
	v_cndmask_b32_e64 v42, 0, 1.0, vcc
	v_fmac_f32_e32 v42, v41, v45
	v_and_b32_e32 v45, 0xffff0000, v73
	v_cmp_eq_u32_e32 vcc, 3, v135
	v_fmac_f32_e32 v42, v44, v45
	v_lshlrev_b32_e32 v47, 16, v82
	v_cndmask_b32_e64 v45, 0, 1.0, vcc
	v_fmac_f32_e32 v45, v41, v46
	v_and_b32_e32 v46, 0xffff0000, v80
	v_fmac_f32_e32 v45, v44, v46
	v_lshlrev_b32_e32 v46, 16, v81
	v_cmp_eq_u32_e32 vcc, 4, v135
	v_fmac_f32_e32 v45, v42, v46
	s_nop 0
	v_cndmask_b32_e64 v46, 0, 1.0, vcc
	v_fmac_f32_e32 v46, v41, v47
	v_and_b32_e32 v47, 0xffff0000, v82
	ds_read_b128 v[108:111], v70 offset:1584
	v_fmac_f32_e32 v46, v44, v47
	v_lshlrev_b32_e32 v47, 16, v83
	v_fmac_f32_e32 v46, v42, v47
	v_and_b32_e32 v47, 0xffff0000, v83
	v_cmp_eq_u32_e32 vcc, 5, v135
	v_fmac_f32_e32 v46, v45, v47
	s_waitcnt lgkmcnt(6)
	v_lshlrev_b32_e32 v48, 16, v84
	v_cndmask_b32_e64 v47, 0, 1.0, vcc
	v_fmac_f32_e32 v47, v41, v48
	v_and_b32_e32 v48, 0xffff0000, v84
	v_fmac_f32_e32 v47, v44, v48
	v_lshlrev_b32_e32 v48, 16, v85
	v_fmac_f32_e32 v47, v42, v48
	v_and_b32_e32 v48, 0xffff0000, v85
	v_fmac_f32_e32 v47, v45, v48
	v_lshlrev_b32_e32 v48, 16, v86
	ds_read2_b64 v[80:83], v70 offset0:200 offset1:218
	v_cmp_eq_u32_e32 vcc, 6, v135
	v_fmac_f32_e32 v47, v46, v48
	s_waitcnt lgkmcnt(6)
	v_lshlrev_b32_e32 v50, 16, v88
	v_cndmask_b32_e64 v48, 0, 1.0, vcc
	v_fmac_f32_e32 v48, v41, v50
	v_and_b32_e32 v50, 0xffff0000, v88
	v_fmac_f32_e32 v48, v44, v50
	v_lshlrev_b32_e32 v50, 16, v89
	v_fmac_f32_e32 v48, v42, v50
	v_and_b32_e32 v50, 0xffff0000, v89
	v_fmac_f32_e32 v48, v45, v50
	v_lshlrev_b32_e32 v50, 16, v90
	v_fmac_f32_e32 v48, v46, v50
	v_and_b32_e32 v50, 0xffff0000, v90
	ds_read_b128 v[84:87], v70 offset:1728
	v_cmp_eq_u32_e32 vcc, 7, v135
	v_fmac_f32_e32 v48, v47, v50
	s_waitcnt lgkmcnt(6)
	v_lshlrev_b32_e32 v51, 16, v92
	v_cndmask_b32_e64 v50, 0, 1.0, vcc
	v_fmac_f32_e32 v50, v41, v51
	v_and_b32_e32 v51, 0xffff0000, v92
	v_fmac_f32_e32 v50, v44, v51
	v_lshlrev_b32_e32 v51, 16, v93
	v_fmac_f32_e32 v50, v42, v51
	v_and_b32_e32 v51, 0xffff0000, v93
	v_fmac_f32_e32 v50, v45, v51
	v_lshlrev_b32_e32 v51, 16, v94
	v_fmac_f32_e32 v50, v46, v51
	v_and_b32_e32 v51, 0xffff0000, v94
	v_fmac_f32_e32 v50, v47, v51
	v_lshlrev_b32_e32 v51, 16, v95
	ds_read_b128 v[88:91], v70 offset:1872
	v_cmp_eq_u32_e32 vcc, 8, v135
	v_fmac_f32_e32 v50, v48, v51
	s_waitcnt lgkmcnt(6)
	v_lshlrev_b32_e32 v53, 16, v96
	v_cndmask_b32_e64 v51, 0, 1.0, vcc
	v_fmac_f32_e32 v51, v41, v53
	v_and_b32_e32 v53, 0xffff0000, v96
	v_fmac_f32_e32 v51, v44, v53
	v_lshlrev_b32_e32 v53, 16, v97
	v_fmac_f32_e32 v51, v42, v53
	v_and_b32_e32 v53, 0xffff0000, v97
	v_fmac_f32_e32 v51, v45, v53
	v_lshlrev_b32_e32 v53, 16, v98
	v_fmac_f32_e32 v51, v46, v53
	v_and_b32_e32 v53, 0xffff0000, v98
	v_fmac_f32_e32 v51, v47, v53
	v_lshlrev_b32_e32 v53, 16, v99
	v_fmac_f32_e32 v51, v48, v53
	v_and_b32_e32 v53, 0xffff0000, v99
	ds_read_b96 v[92:94], v70 offset:1888
	v_cmp_eq_u32_e32 vcc, 9, v135
	v_fmac_f32_e32 v51, v50, v53
	s_waitcnt lgkmcnt(6)
	v_lshlrev_b32_e32 v58, 16, v100
	v_cndmask_b32_e64 v53, 0, 1.0, vcc
	v_fmac_f32_e32 v53, v41, v58
	v_and_b32_e32 v54, 0xffff0000, v100
	v_fmac_f32_e32 v53, v44, v54
	v_lshlrev_b32_e32 v54, 16, v101
	v_fmac_f32_e32 v53, v42, v54
	v_and_b32_e32 v54, 0xffff0000, v101
	v_fmac_f32_e32 v53, v45, v54
	v_lshlrev_b32_e32 v54, 16, v102
	v_fmac_f32_e32 v53, v46, v54
	v_and_b32_e32 v54, 0xffff0000, v102
	v_fmac_f32_e32 v53, v47, v54
	v_lshlrev_b32_e32 v54, 16, v103
	v_fmac_f32_e32 v53, v48, v54
	v_and_b32_e32 v54, 0xffff0000, v103
	ds_read_b128 v[96:99], v70 offset:2016
	v_fmac_f32_e32 v53, v50, v54
	v_lshlrev_b32_e32 v54, 16, v76
	v_cmp_eq_u32_e32 vcc, 10, v135
	v_fmac_f32_e32 v53, v51, v54
	s_waitcnt lgkmcnt(6)
	v_lshlrev_b32_e32 v55, 16, v104
	v_cndmask_b32_e64 v54, 0, 1.0, vcc
	v_fmac_f32_e32 v54, v41, v55
	v_and_b32_e32 v55, 0xffff0000, v104
	v_fmac_f32_e32 v54, v44, v55
	v_lshlrev_b32_e32 v55, 16, v105
	v_fmac_f32_e32 v54, v42, v55
	v_and_b32_e32 v55, 0xffff0000, v105
	v_fmac_f32_e32 v54, v45, v55
	v_lshlrev_b32_e32 v55, 16, v106
	v_fmac_f32_e32 v54, v46, v55
	v_and_b32_e32 v55, 0xffff0000, v106
	v_fmac_f32_e32 v54, v47, v55
	v_lshlrev_b32_e32 v55, 16, v107
	v_fmac_f32_e32 v54, v48, v55
	v_and_b32_e32 v55, 0xffff0000, v107
	v_fmac_f32_e32 v54, v50, v55
	v_lshlrev_b32_e32 v55, 16, v77
	v_fmac_f32_e32 v54, v51, v55
	v_and_b32_e32 v55, 0xffff0000, v77
	ds_read_b96 v[76:78], v70 offset:2032
	v_cmp_eq_u32_e32 vcc, 11, v135
	v_fmac_f32_e32 v54, v53, v55
	s_waitcnt lgkmcnt(6)
	v_lshlrev_b32_e32 v63, 16, v108
	v_cndmask_b32_e64 v55, 0, 1.0, vcc
	v_fmac_f32_e32 v55, v41, v63
	v_and_b32_e32 v56, 0xffff0000, v108
	v_fmac_f32_e32 v55, v44, v56
	v_lshlrev_b32_e32 v56, 16, v109
	v_fmac_f32_e32 v55, v42, v56
	v_and_b32_e32 v56, 0xffff0000, v109
	v_fmac_f32_e32 v55, v45, v56
	v_lshlrev_b32_e32 v56, 16, v110
	v_fmac_f32_e32 v55, v46, v56
	v_and_b32_e32 v56, 0xffff0000, v110
	v_fmac_f32_e32 v55, v47, v56
	v_lshlrev_b32_e32 v56, 16, v111
	v_fmac_f32_e32 v55, v48, v56
	v_and_b32_e32 v56, 0xffff0000, v111
	v_fmac_f32_e32 v55, v50, v56
	s_waitcnt lgkmcnt(5)
	v_lshlrev_b32_e32 v56, 16, v80
	v_fmac_f32_e32 v55, v51, v56
	v_and_b32_e32 v56, 0xffff0000, v80
	v_fmac_f32_e32 v55, v53, v56
	v_lshlrev_b32_e32 v56, 16, v81
	v_fmac_f32_e32 v55, v54, v56
	v_cmp_eq_u32_e32 vcc, 12, v135
	s_waitcnt lgkmcnt(4)
	v_lshlrev_b32_e32 v64, 16, v84
	v_cndmask_b32_e64 v63, 0, 1.0, vcc
	v_fmac_f32_e32 v63, v41, v64
	v_and_b32_e32 v56, 0xffff0000, v84
	v_fmac_f32_e32 v63, v44, v56
	v_lshlrev_b32_e32 v56, 16, v85
	v_fmac_f32_e32 v63, v42, v56
	v_and_b32_e32 v56, 0xffff0000, v85
	v_fmac_f32_e32 v63, v45, v56
	v_lshlrev_b32_e32 v56, 16, v86
	v_fmac_f32_e32 v63, v46, v56
	v_and_b32_e32 v56, 0xffff0000, v86
	v_fmac_f32_e32 v63, v47, v56
	v_lshlrev_b32_e32 v56, 16, v87
	v_fmac_f32_e32 v63, v48, v56
	v_and_b32_e32 v56, 0xffff0000, v87
	v_fmac_f32_e32 v63, v50, v56
	v_lshlrev_b32_e32 v56, 16, v82
	v_fmac_f32_e32 v63, v51, v56
	v_and_b32_e32 v56, 0xffff0000, v82
	v_fmac_f32_e32 v63, v53, v56
	v_lshlrev_b32_e32 v56, 16, v83
	v_fmac_f32_e32 v63, v54, v56
	v_and_b32_e32 v56, 0xffff0000, v83
	v_fmac_f32_e32 v63, v55, v56
	v_cmp_eq_u32_e32 vcc, 13, v135
	s_waitcnt lgkmcnt(3)
	v_lshlrev_b32_e32 v67, 16, v88
	v_cndmask_b32_e64 v68, 0, 1.0, vcc
	v_fmac_f32_e32 v68, v41, v67
	v_and_b32_e32 v56, 0xffff0000, v88
	v_fmac_f32_e32 v68, v44, v56
	v_lshlrev_b32_e32 v56, 16, v89
	v_fmac_f32_e32 v68, v42, v56
	v_and_b32_e32 v56, 0xffff0000, v89
	v_fmac_f32_e32 v68, v45, v56
	v_lshlrev_b32_e32 v56, 16, v90
	v_fmac_f32_e32 v68, v46, v56
	v_and_b32_e32 v56, 0xffff0000, v90
	v_fmac_f32_e32 v68, v47, v56
	v_lshlrev_b32_e32 v56, 16, v91
	v_fmac_f32_e32 v68, v48, v56
	v_and_b32_e32 v56, 0xffff0000, v91
	v_fmac_f32_e32 v68, v50, v56
	s_waitcnt lgkmcnt(2)
	v_lshlrev_b32_e32 v56, 16, v92
	v_fmac_f32_e32 v68, v51, v56
	v_and_b32_e32 v56, 0xffff0000, v92
	v_fmac_f32_e32 v68, v53, v56
	v_lshlrev_b32_e32 v56, 16, v93
	v_fmac_f32_e32 v68, v54, v56
	v_and_b32_e32 v56, 0xffff0000, v93
	v_fmac_f32_e32 v68, v55, v56
	v_lshlrev_b32_e32 v56, 16, v94
	v_fmac_f32_e32 v68, v63, v56
	v_cmp_eq_u32_e32 vcc, 14, v135
	s_waitcnt lgkmcnt(1)
	v_lshlrev_b32_e32 v49, 16, v96
	v_cndmask_b32_e64 v69, 0, 1.0, vcc
	v_fmac_f32_e32 v69, v41, v49
	v_and_b32_e32 v49, 0xffff0000, v96
	v_fmac_f32_e32 v69, v44, v49
	v_lshlrev_b32_e32 v49, 16, v97
	v_fmac_f32_e32 v69, v42, v49
	v_and_b32_e32 v49, 0xffff0000, v97
	v_fmac_f32_e32 v69, v45, v49
	v_lshlrev_b32_e32 v49, 16, v98
	v_fmac_f32_e32 v69, v46, v49
	v_and_b32_e32 v49, 0xffff0000, v98
	v_fmac_f32_e32 v69, v47, v49
	v_lshlrev_b32_e32 v49, 16, v99
	v_fmac_f32_e32 v69, v48, v49
	v_and_b32_e32 v49, 0xffff0000, v99
	v_fmac_f32_e32 v69, v50, v49
	s_waitcnt lgkmcnt(0)
	v_lshlrev_b32_e32 v49, 16, v76
	v_fmac_f32_e32 v69, v51, v49
	v_and_b32_e32 v49, 0xffff0000, v76
	v_fmac_f32_e32 v69, v53, v49
	v_lshlrev_b32_e32 v49, 16, v77
	v_fmac_f32_e32 v69, v54, v49
	v_and_b32_e32 v49, 0xffff0000, v77
	v_or_b32_e32 v56, 15, v137
	v_fmac_f32_e32 v69, v55, v49
	v_lshlrev_b32_e32 v49, 16, v78
	v_mad_u64_u32 v[64:65], s[4:5], v56, s96, v[40:41]
	v_fmac_f32_e32 v69, v63, v49
	v_and_b32_e32 v49, 0xffff0000, v78
	ds_read_b128 v[56:59], v64 offset:64512
	ds_read_b128 v[64:67], v64 offset:64528
	v_cmp_eq_u32_e32 vcc, 15, v135
	v_fmac_f32_e32 v69, v68, v49
	s_waitcnt lgkmcnt(1)
	v_lshlrev_b32_e32 v40, 16, v56
	v_cndmask_b32_e64 v49, 0, 1.0, vcc
	v_fmac_f32_e32 v49, v41, v40
	v_and_b32_e32 v40, 0xffff0000, v56
	v_fmac_f32_e32 v49, v44, v40
	v_lshlrev_b32_e32 v40, 16, v57
	v_fmac_f32_e32 v49, v42, v40
	v_and_b32_e32 v40, 0xffff0000, v57
	v_fmac_f32_e32 v49, v45, v40
	v_lshlrev_b32_e32 v40, 16, v58
	v_fmac_f32_e32 v49, v46, v40
	v_and_b32_e32 v40, 0xffff0000, v58
	v_fmac_f32_e32 v49, v47, v40
	v_lshlrev_b32_e32 v40, 16, v59
	v_fmac_f32_e32 v49, v48, v40
	v_and_b32_e32 v40, 0xffff0000, v59
	v_fmac_f32_e32 v49, v50, v40
	s_waitcnt lgkmcnt(0)
	v_lshlrev_b32_e32 v40, 16, v64
	v_fmac_f32_e32 v49, v51, v40
	v_and_b32_e32 v40, 0xffff0000, v64
	v_fmac_f32_e32 v49, v53, v40
	v_lshlrev_b32_e32 v40, 16, v65
	v_fmac_f32_e32 v49, v54, v40
	v_and_b32_e32 v40, 0xffff0000, v65
	v_fmac_f32_e32 v49, v55, v40
	v_lshlrev_b32_e32 v40, 16, v66
	v_fmac_f32_e32 v49, v63, v40
	v_and_b32_e32 v40, 0xffff0000, v66
	v_fmac_f32_e32 v49, v68, v40
	v_lshlrev_b32_e32 v40, 16, v67
	v_fmac_f32_e32 v49, v69, v40
	v_lshlrev_b32_e32 v40, 9, v139
	v_add3_u32 v40, s97, v40, v61
	ds_write_b16_d16_hi v40, v41
	v_bfe_u32 v41, v44, 16, 1
	v_add3_u32 v41, v44, v41, s93
	ds_write_b16_d16_hi v40, v41 offset:32
	v_bfe_u32 v41, v42, 16, 1
	v_add3_u32 v41, v42, v41, s93
	ds_write_b16_d16_hi v40, v41 offset:64
	v_bfe_u32 v41, v45, 16, 1
	v_add3_u32 v41, v45, v41, s93
	ds_write_b16_d16_hi v40, v41 offset:96
	v_bfe_u32 v41, v46, 16, 1
	v_add3_u32 v41, v46, v41, s93
	ds_write_b16_d16_hi v40, v41 offset:128
	v_bfe_u32 v41, v47, 16, 1
	v_add3_u32 v41, v47, v41, s93
	ds_write_b16_d16_hi v40, v41 offset:160
	v_bfe_u32 v41, v48, 16, 1
	v_add3_u32 v41, v48, v41, s93
	ds_write_b16_d16_hi v40, v41 offset:192
	v_bfe_u32 v41, v50, 16, 1
	v_add3_u32 v41, v50, v41, s93
	ds_write_b16_d16_hi v40, v41 offset:224
	v_bfe_u32 v41, v51, 16, 1
	v_add3_u32 v41, v51, v41, s93
	ds_write_b16_d16_hi v40, v41 offset:256
	v_bfe_u32 v41, v53, 16, 1
	v_add3_u32 v41, v53, v41, s93
	ds_write_b16_d16_hi v40, v41 offset:288
	v_bfe_u32 v41, v54, 16, 1
	v_add3_u32 v41, v54, v41, s93
	ds_write_b16_d16_hi v40, v41 offset:320
	v_bfe_u32 v41, v55, 16, 1
	v_add3_u32 v41, v55, v41, s93
	ds_write_b16_d16_hi v40, v41 offset:352
	v_bfe_u32 v41, v63, 16, 1
	v_add3_u32 v41, v63, v41, s93
	ds_write_b16_d16_hi v40, v41 offset:384
	v_bfe_u32 v41, v68, 16, 1
	v_add3_u32 v41, v68, v41, s93
	ds_write_b16_d16_hi v40, v41 offset:416
	v_bfe_u32 v41, v69, 16, 1
	v_add3_u32 v41, v69, v41, s93
	ds_write_b16_d16_hi v40, v41 offset:448
	v_bfe_u32 v41, v49, 16, 1
	v_add3_u32 v41, v49, v41, s93
	ds_write_b16_d16_hi v40, v41 offset:480
	s_waitcnt lgkmcnt(0)

.LBB0_1030:
	v_or_b32_e32 v0, s74, v105
	v_lshlrev_b32_e32 v72, 1, v0
	v_lshlrev_b32_e32 v22, 1, v104
	s_and_saveexec_b64 s[4:5], s[0:1]
	s_cbranch_execz .LBB0_1032
	v_add_u32_e32 v68, 0, v76
	v_add_u32_e32 v136, v68, v96
	v_add_u32_e32 v137, 0, v96
	ds_read2_b64 v[140:143], v136 offset1:4
	v_add_u32_e32 v138, v137, v76
	ds_read2st64_b64 v[148:151], v138 offset0:18 offset1:41
	v_add_u32_e32 v139, 0, v98
	ds_read_b128 v[152:155], v139 offset:11520
	ds_read_b128 v[156:159], v139 offset:35072
	ds_read2_b64 v[160:163], v136 offset0:8 offset1:12
	v_add_u32_e32 v165, 0x800, v136
	ds_read2_b64 v[168:171], v165 offset0:32 offset1:36
	v_add_u32_e32 v166, v137, v92
	ds_read2st64_b64 v[176:179], v166 offset0:18 offset1:41
	v_add_u32_e32 v167, 0, v91
	ds_read_b128 v[180:183], v167 offset:11520
	ds_read2_b64 v[184:187], v165 offset0:40 offset1:44
	v_add_u32_e32 v165, 0x1000, v136
	v_add_u32_e32 v172, v137, v90
	ds_read2_b64 v[188:191], v165 offset0:64 offset1:68
	ds_read2st64_b64 v[192:195], v172 offset0:18 offset1:41
	v_add_u32_e32 v173, 0, v89
	ds_read_b128 v[196:199], v167 offset:35072
	ds_read_b128 v[200:203], v173 offset:11520
	s_waitcnt lgkmcnt(11)
	v_lshlrev_b32_e32 v24, 16, v148
	v_and_b32_e32 v25, 0xffff0000, v148
	v_lshlrev_b32_e32 v6, 16, v149
	v_and_b32_e32 v7, 0xffff0000, v149
	v_cvt_pk_bf16_f32 v0, v40, v41
	v_cvt_pk_bf16_f32 v1, v42, v43
	v_cvt_pk_bf16_f32 v2, v36, v37
	v_cvt_pk_bf16_f32 v3, v38, v39
	s_waitcnt lgkmcnt(10)
	v_pk_fma_f32 v[12:13], v[42:43], v[154:155], v[6:7]
	v_pk_fma_f32 v[10:11], v[40:41], v[152:153], v[24:25]
	ds_read2_b64 v[152:155], v165 offset0:72 offset1:76
	v_mfma_f32_16x16x32_bf16 v[10:13], v[140:143], v[0:3], v[10:13]
	v_cvt_pk_bf16_f32 v4, v44, v45
	v_cvt_pk_bf16_f32 v5, v46, v47
	v_cvt_pk_bf16_f32 v6, v48, v49
	v_cvt_pk_bf16_f32 v7, v50, v51
	v_add_u32_e32 v140, v137, v88
	ds_read2st64_b64 v[204:207], v140 offset0:18 offset1:41
	s_waitcnt lgkmcnt(10)
	v_mfma_f32_16x16x32_bf16 v[10:13], v[160:163], v[4:7], v[10:13]
	v_add_u32_e32 v137, 0, v86
	ds_read_b128 v[160:163], v173 offset:35072
	ds_read_b128 v[208:211], v137 offset:11520
	s_waitcnt lgkmcnt(10)
	v_lshlrev_b32_e32 v24, 16, v176
	v_and_b32_e32 v25, 0xffff0000, v176
	v_lshlrev_b32_e32 v14, 16, v177
	v_and_b32_e32 v15, 0xffff0000, v177
	s_waitcnt lgkmcnt(9)
	v_pk_fma_f32 v[20:21], v[38:39], v[182:183], v[14:15]
	v_pk_fma_f32 v[18:19], v[36:37], v[180:181], v[24:25]
	v_lshl_add_u64 v[14:15], s[62:63], 0, v[72:73]
	v_mov_b32_e32 v23, v73
	v_mfma_f32_16x16x32_bf16 v[18:21], v[168:171], v[0:3], v[18:21]
	v_lshl_add_u64 v[14:15], v[14:15], 0, v[22:23]
	s_waitcnt lgkmcnt(8)
	v_mfma_f32_16x16x32_bf16 v[18:21], v[184:187], v[4:7], v[18:21]
	s_waitcnt lgkmcnt(6)
	v_lshlrev_b32_e32 v24, 16, v192
	v_and_b32_e32 v25, 0xffff0000, v192
	v_lshlrev_b32_e32 v34, 16, v193
	v_and_b32_e32 v35, 0xffff0000, v193
	s_waitcnt lgkmcnt(4)
	v_pk_fma_f32 v[40:41], v[46:47], v[202:203], v[34:35]
	v_pk_fma_f32 v[38:39], v[44:45], v[200:201], v[24:25]
	v_add_u32_e32 v87, v68, v87
	v_mfma_f32_16x16x32_bf16 v[38:41], v[188:191], v[0:3], v[38:41]
	ds_read2_b64 v[168:171], v87 offset1:4
	ds_read2_b64 v[180:183], v87 offset0:8 offset1:12
	ds_read_b128 v[184:187], v137 offset:35072
	v_add_u32_e32 v141, 0x2800, v136
	ds_read2_b64 v[188:191], v141 offset0:192 offset1:196
	ds_read_b128 v[200:203], v139 offset:23296
	ds_read_b64 v[142:143], v166 offset:32768
	ds_read2_b64 v[212:215], v141 offset0:200 offset1:204
	ds_read_b64 v[216:217], v138 offset:32768
	s_waitcnt lgkmcnt(11)
	v_mfma_f32_16x16x32_bf16 v[38:41], v[152:155], v[4:7], v[38:41]
	ds_read_b128 v[152:155], v167 offset:23296
	v_lshl_add_u64 v[24:25], v[14:15], 0, s[14:15]
	s_waitcnt lgkmcnt(11)
	v_lshlrev_b32_e32 v14, 16, v204
	v_and_b32_e32 v15, 0xffff0000, v204
	v_lshlrev_b32_e32 v42, 16, v205
	v_and_b32_e32 v43, 0xffff0000, v205
	s_waitcnt lgkmcnt(9)
	v_pk_fma_f32 v[50:51], v[50:51], v[210:211], v[42:43]
	v_pk_fma_f32 v[48:49], v[48:49], v[208:209], v[14:15]
	v_add_u32_e32 v138, 0x3000, v136
	ds_read2_b64 v[208:211], v138 offset0:224 offset1:228
	ds_read2_b64 v[220:223], v138 offset0:232 offset1:236
	s_waitcnt lgkmcnt(10)
	v_mfma_f32_16x16x32_bf16 v[46:49], v[168:171], v[0:3], v[48:51]
	v_add_u32_e32 v138, 0x4000, v136
	ds_read_b128 v[168:171], v173 offset:23296
	v_add_co_u32_e32 v34, vcc, s69, v24
	s_waitcnt lgkmcnt(10)
	v_mfma_f32_16x16x32_bf16 v[46:49], v[180:183], v[4:7], v[46:49]
	ds_read2_b64 v[180:183], v138 offset1:4
	ds_read2_b64 v[224:227], v138 offset0:8 offset1:12
	v_addc_co_u32_e32 v35, vcc, 0, v25, vcc
	global_store_dwordx2 v[34:35], v[0:1], off nt
	v_lshlrev_b32_e32 v0, 16, v150
	v_and_b32_e32 v1, 0xffff0000, v150
	v_lshlrev_b32_e32 v8, 16, v151
	v_and_b32_e32 v9, 0xffff0000, v151
	v_cvt_pk_bf16_f32 v50, v10, v11
	v_cvt_pk_bf16_f32 v51, v12, v13
	v_cvt_pk_bf16_f32 v52, v18, v19
	v_cvt_pk_bf16_f32 v53, v20, v21
	s_waitcnt lgkmcnt(9)
	v_pk_fma_f32 v[12:13], v[12:13], v[202:203], v[8:9]
	v_pk_fma_f32 v[10:11], v[10:11], v[200:201], v[0:1]
	ds_read_b64 v[138:139], v172 offset:32768
	v_add_u32_e32 v141, 0x2800, v87
	ds_read_b128 v[148:151], v137 offset:23296
	v_mfma_f32_16x16x32_bf16 v[8:11], v[188:191], v[50:53], v[10:13]
	v_lshlrev_b32_e32 v0, 16, v178
	v_and_b32_e32 v1, 0xffff0000, v178
	v_lshlrev_b32_e32 v16, 16, v179
	ds_read_b64 v[166:167], v140 offset:32768
	ds_read2_b64 v[188:191], v141 offset0:192 offset1:196
	ds_read2_b64 v[200:203], v141 offset0:200 offset1:204
	v_and_b32_e32 v17, 0xffff0000, v179
	s_waitcnt lgkmcnt(10)
	v_pk_fma_f32 v[14:15], v[20:21], v[154:155], v[16:17]
	v_pk_fma_f32 v[12:13], v[18:19], v[152:153], v[0:1]
	v_cvt_pk_bf16_f32 v60, v38, v39
	v_cvt_pk_bf16_f32 v61, v40, v41
	s_waitcnt lgkmcnt(9)
	v_mfma_f32_16x16x32_bf16 v[12:15], v[208:211], v[50:53], v[12:15]
	v_cvt_pk_bf16_f32 v62, v46, v47
	v_cvt_pk_bf16_f32 v63, v48, v49
	global_store_dwordx2 v[34:35], v[2:3], off offset:32 nt
	global_store_dwordx2 v[34:35], v[4:5], off offset:64 nt
	global_store_dwordx2 v[34:35], v[6:7], off offset:96 nt
	s_waitcnt lgkmcnt(8)
	v_mfma_f32_16x16x32_bf16 v[0:3], v[220:223], v[60:63], v[12:15]
	v_add_u32_e32 v137, 0x5800, v136
	ds_read2_b64 v[152:155], v137 offset0:128 offset1:132
	v_lshlrev_b32_e32 v20, 16, v194
	v_and_b32_e32 v21, 0xffff0000, v194
	ds_read2_b64 v[176:179], v137 offset0:136 offset1:140
	v_lshlrev_b32_e32 v34, 16, v195
	v_and_b32_e32 v35, 0xffff0000, v195
	s_waitcnt lgkmcnt(9)
	v_pk_fma_f32 v[6:7], v[40:41], v[170:171], v[34:35]
	v_pk_fma_f32 v[4:5], v[38:39], v[168:169], v[20:21]
	v_add_u32_e32 v137, 0x6000, v136
	ds_read2_b64 v[168:171], v137 offset0:160 offset1:164
	ds_read2_b64 v[192:195], v137 offset0:168 offset1:172
	s_waitcnt lgkmcnt(10)
	v_mfma_f32_16x16x32_bf16 v[4:7], v[180:183], v[50:53], v[4:7]
	v_add_u32_e32 v137, 0x6800, v136
	ds_read2_b64 v[180:183], v137 offset0:192 offset1:196
	ds_read2_b64 v[208:211], v137 offset0:200 offset1:204
	s_waitcnt lgkmcnt(11)
	v_mfma_f32_16x16x32_bf16 v[4:7], v[224:227], v[60:63], v[4:7]
	v_lshlrev_b32_e32 v38, 16, v206
	v_and_b32_e32 v39, 0xffff0000, v206
	v_lshlrev_b32_e32 v40, 16, v207
	v_and_b32_e32 v41, 0xffff0000, v207
	s_waitcnt lgkmcnt(9)
	v_pk_fma_f32 v[14:15], v[48:49], v[150:151], v[40:41]
	v_pk_fma_f32 v[12:13], v[46:47], v[148:149], v[38:39]
	v_add_co_u32_e32 v20, vcc, s70, v24
	s_waitcnt lgkmcnt(7)
	v_mfma_f32_16x16x32_bf16 v[12:15], v[188:191], v[50:53], v[12:15]
	v_addc_co_u32_e32 v21, vcc, 0, v25, vcc
	global_store_dwordx2 v[20:21], v[50:51], off nt
	global_store_dwordx2 v[20:21], v[52:53], off offset:32 nt
	global_store_dwordx2 v[20:21], v[60:61], off offset:64 nt
	global_store_dwordx2 v[20:21], v[62:63], off offset:96 nt
	s_waitcnt lgkmcnt(6)
	v_mfma_f32_16x16x32_bf16 v[12:15], v[200:203], v[60:63], v[12:15]
	v_lshlrev_b32_e32 v20, 16, v216
	v_mfma_f32_16x16x32_bf16 v[8:11], v[212:215], v[60:63], v[8:11]
	v_and_b32_e32 v21, 0xffff0000, v216
	v_lshlrev_b32_e32 v28, 16, v217
	v_and_b32_e32 v29, 0xffff0000, v217
	v_cvt_pk_bf16_f32 v18, v0, v1
	v_cvt_pk_bf16_f32 v19, v2, v3
	s_nop 2
	v_cvt_pk_bf16_f32 v16, v8, v9
	v_cvt_pk_bf16_f32 v17, v10, v11
	v_pk_fma_f32 v[10:11], v[10:11], v[158:159], v[28:29]
	v_pk_fma_f32 v[8:9], v[8:9], v[156:157], v[20:21]
	s_waitcnt lgkmcnt(5)
	v_mfma_f32_16x16x32_bf16 v[8:11], v[152:155], v[16:19], v[8:11]
	v_cvt_pk_bf16_f32 v48, v4, v5
	v_cvt_pk_bf16_f32 v49, v6, v7
	v_cvt_pk_bf16_f32 v50, v12, v13
	v_cvt_pk_bf16_f32 v51, v14, v15
	v_lshlrev_b32_e32 v20, 16, v142
	v_and_b32_e32 v21, 0xffff0000, v142
	s_waitcnt lgkmcnt(4)
	v_mfma_f32_16x16x32_bf16 v[40:43], v[176:179], v[48:51], v[8:11]
	v_fma_f32 v0, v0, v196, v20
	v_fma_f32 v1, v1, v197, v21
	v_add_co_u32_e32 v20, vcc, s71, v24
	v_lshlrev_b32_e32 v8, 16, v143
	v_and_b32_e32 v9, 0xffff0000, v143
	v_pk_fma_f32 v[2:3], v[2:3], v[198:199], v[8:9]
	s_waitcnt lgkmcnt(3)
	v_mfma_f32_16x16x32_bf16 v[0:3], v[168:171], v[16:19], v[0:3]
	v_addc_co_u32_e32 v21, vcc, 0, v25, vcc
	s_waitcnt lgkmcnt(2)
	v_mfma_f32_16x16x32_bf16 v[36:39], v[192:195], v[48:51], v[0:3]
	v_lshlrev_b32_e32 v8, 16, v138
	s_nop 2
	v_and_b32_e32 v9, 0xffff0000, v138
	v_lshlrev_b32_e32 v10, 16, v139
	v_and_b32_e32 v11, 0xffff0000, v139
	v_pk_fma_f32 v[6:7], v[6:7], v[162:163], v[10:11]
	v_pk_fma_f32 v[4:5], v[4:5], v[160:161], v[8:9]
	v_add_u32_e32 v23, 0x5800, v87
	ds_read2_b64 v[8:11], v23 offset0:128 offset1:132
	s_waitcnt lgkmcnt(2)
	v_mfma_f32_16x16x32_bf16 v[4:7], v[180:183], v[16:19], v[4:7]
	global_store_dwordx2 v[20:21], v[16:17], off nt
	s_waitcnt lgkmcnt(1)
	v_mfma_f32_16x16x32_bf16 v[44:47], v[208:211], v[48:51], v[4:7]
	ds_read2_b64 v[0:3], v23 offset0:136 offset1:140
	global_store_dwordx2 v[20:21], v[18:19], off offset:32 nt
	global_store_dwordx2 v[20:21], v[48:49], off offset:64 nt
	global_store_dwordx2 v[20:21], v[50:51], off offset:96 nt
	s_nop 0
	v_lshlrev_b32_e32 v4, 16, v166
	v_and_b32_e32 v5, 0xffff0000, v166
	v_lshlrev_b32_e32 v6, 16, v167
	v_and_b32_e32 v7, 0xffff0000, v167
	v_pk_fma_f32 v[6:7], v[14:15], v[186:187], v[6:7]
	v_pk_fma_f32 v[4:5], v[12:13], v[184:185], v[4:5]
	s_nop 0
	s_waitcnt lgkmcnt(1)
	v_mfma_f32_16x16x32_bf16 v[4:7], v[8:11], v[16:19], v[4:7]
	s_waitcnt lgkmcnt(0)
	v_mfma_f32_16x16x32_bf16 v[48:51], v[0:3], v[48:51], v[4:7]
